# grid-barrier census (first barrier): sixteen per-XCC counter loads issued together, one wait, instead of one at a time
# baseline (speedup 1.0000x reference)
; __device__ __forceinline__ unsigned xb_ld(unsigned* p)              { return __hip_atomic_load(p, __ATOMIC_RELAXED, __HIP_MEMORY_SCOPE_AGENT); }
; __device__ __forceinline__ void xcd_barrier_complete(unsigned* bar, unsigned x, unsigned& nloc, unsigned& nx) {
;     ...
;     for (;;) {
;         sum = 0u; cnt = 0u; mine = 0u;
; #pragma unroll
;         for (unsigned j = 0; j < 16; ++j) { const unsigned c = xb_ld(&bar[XB_XCNT(j)]); sum += c; cnt += (c > 0u) ? 1u : 0u; mine = (j == x) ? c : mine; }
;         if (sum == G) break;
;         __builtin_amdgcn_s_sleep(1);
;         if ((++sp & 255u) == 0u) { if (xb_ld(&bar[XB_TMO])) break; if (sp > XB_SPIN_CAP) { atomicAdd(&bar[XB_TMO], 1u); break; } }
;     }
.LBB0_423:
	v_readlane_b32 s6, v254, 1
	v_readlane_b32 s7, v254, 2
	s_waitcnt lgkmcnt(0)
	global_load_dword v1, v0, s[60:61] sc1
	s_mov_b64 s[16:17], -1
	s_mov_b64 s[20:21], -1
	s_nop 0
	global_load_dword v2, v0, s[6:7] sc1
	v_readlane_b32 s6, v254, 3
	v_readlane_b32 s7, v254, 4
	s_nop 4
	global_load_dword v3, v0, s[6:7] sc1
	v_readlane_b32 s6, v254, 5
	v_readlane_b32 s7, v254, 6
	s_nop 4
	global_load_dword v4, v0, s[6:7] sc1
	v_readlane_b32 s6, v254, 7
	v_readlane_b32 s7, v254, 8
	s_nop 4
	global_load_dword v5, v0, s[6:7] sc1
	v_readlane_b32 s6, v254, 9
	v_readlane_b32 s7, v254, 10
	s_nop 4
	global_load_dword v6, v0, s[6:7] sc1
	v_readlane_b32 s6, v254, 11
	v_readlane_b32 s7, v254, 12
	s_nop 4
	global_load_dword v7, v0, s[6:7] sc1
	v_readlane_b32 s6, v254, 13
	v_readlane_b32 s7, v254, 14
	s_nop 4
	global_load_dword v8, v0, s[6:7] sc1
	v_readlane_b32 s6, v254, 15
	v_readlane_b32 s7, v254, 16
	s_nop 4
	global_load_dword v9, v0, s[6:7] sc1
	v_readlane_b32 s6, v254, 17
	v_readlane_b32 s7, v254, 18
	s_nop 4
	global_load_dword v10, v0, s[6:7] sc1
	v_readlane_b32 s6, v254, 19
	v_readlane_b32 s7, v254, 20
	s_nop 4
	global_load_dword v11, v0, s[6:7] sc1
	v_readlane_b32 s6, v254, 21
	v_readlane_b32 s7, v254, 22
	s_nop 4
	global_load_dword v12, v0, s[6:7] sc1
	v_readlane_b32 s6, v254, 23
	v_readlane_b32 s7, v254, 24
	s_nop 4
	global_load_dword v13, v0, s[6:7] sc1
	v_readlane_b32 s6, v254, 25
	v_readlane_b32 s7, v254, 26
	s_nop 4
	global_load_dword v14, v0, s[6:7] sc1
	v_readlane_b32 s6, v254, 27
	v_readlane_b32 s7, v254, 28
	s_nop 4
	global_load_dword v15, v0, s[6:7] sc1
	v_readlane_b32 s6, v254, 29
	v_readlane_b32 s7, v254, 30
	s_nop 4
	global_load_dword v16, v0, s[6:7] sc1
	s_waitcnt vmcnt(0)
	v_add_u32_e32 v17, v2, v1
	v_add_u32_e32 v17, v17, v3
	v_add_u32_e32 v17, v17, v4
	v_add_u32_e32 v17, v17, v5
	v_add_u32_e32 v17, v17, v6
	v_add_u32_e32 v17, v17, v7
	v_add_u32_e32 v17, v17, v8
	v_add_u32_e32 v17, v17, v9
	v_add_u32_e32 v17, v17, v10
	v_add_u32_e32 v17, v17, v11
	v_add_u32_e32 v17, v17, v12
	v_add_u32_e32 v17, v17, v13
	v_add_u32_e32 v17, v17, v14
	v_add_u32_e32 v17, v17, v15
	v_add_u32_e32 v17, v17, v16
	v_cmp_eq_u32_e32 vcc, s62, v17
	s_cbranch_vccnz .LBB0_422
	s_and_b32 s6, s5, 0xff
	s_cmp_eq_u32 s6, 0
	s_mov_b64 s[24:25], -1
	s_sleep 1
	s_cbranch_scc1 .LBB0_427
	s_and_b64 vcc, exec, s[24:25]
	s_cbranch_vccz .LBB0_422

; __device__ __forceinline__ unsigned xb_ld(unsigned* p)              { return __hip_atomic_load(p, __ATOMIC_RELAXED, __HIP_MEMORY_SCOPE_AGENT); }
; __device__ __forceinline__ void xcd_barrier_complete(unsigned* bar, unsigned x, unsigned& nloc, unsigned& nx) {
;     ...
;     for (;;) {
;         sum = 0u; cnt = 0u; mine = 0u;
; #pragma unroll
;         for (unsigned j = 0; j < 16; ++j) { const unsigned c = xb_ld(&bar[XB_XCNT(j)]); sum += c; cnt += (c > 0u) ? 1u : 0u; mine = (j == x) ? c : mine; }
;         if (sum == G) break;
;         __builtin_amdgcn_s_sleep(1);
;         if ((++sp & 255u) == 0u) { if (xb_ld(&bar[XB_TMO])) break; if (sp > XB_SPIN_CAP) { atomicAdd(&bar[XB_TMO], 1u); break; } }
;     }
.LBB0_487:
	v_readlane_b32 s6, v254, 1
	v_readlane_b32 s7, v254, 2
	global_load_dword v1, v0, s[60:61] sc1
	s_mov_b64 s[16:17], -1
	s_mov_b64 s[20:21], -1
	s_waitcnt lgkmcnt(0)
	s_nop 0
	global_load_dword v2, v0, s[6:7] sc1
	v_readlane_b32 s6, v254, 3
	v_readlane_b32 s7, v254, 4
	s_nop 4
	global_load_dword v3, v0, s[6:7] sc1
	v_readlane_b32 s6, v254, 5
	v_readlane_b32 s7, v254, 6
	s_nop 4
	global_load_dword v4, v0, s[6:7] sc1
	v_readlane_b32 s6, v254, 7
	v_readlane_b32 s7, v254, 8
	s_nop 4
	global_load_dword v5, v0, s[6:7] sc1
	v_readlane_b32 s6, v254, 9
	v_readlane_b32 s7, v254, 10
	s_nop 4
	global_load_dword v6, v0, s[6:7] sc1
	v_readlane_b32 s6, v254, 11
	v_readlane_b32 s7, v254, 12
	s_nop 4
	global_load_dword v7, v0, s[6:7] sc1
	v_readlane_b32 s6, v254, 13
	v_readlane_b32 s7, v254, 14
	s_nop 4
	global_load_dword v8, v0, s[6:7] sc1
	v_readlane_b32 s6, v254, 15
	v_readlane_b32 s7, v254, 16
	s_nop 4
	global_load_dword v9, v0, s[6:7] sc1
	v_readlane_b32 s6, v254, 17
	v_readlane_b32 s7, v254, 18
	s_nop 4
	global_load_dword v10, v0, s[6:7] sc1
	v_readlane_b32 s6, v254, 19
	v_readlane_b32 s7, v254, 20
	s_nop 4
	global_load_dword v11, v0, s[6:7] sc1
	v_readlane_b32 s6, v254, 21
	v_readlane_b32 s7, v254, 22
	s_nop 4
	global_load_dword v12, v0, s[6:7] sc1
	v_readlane_b32 s6, v254, 23
	v_readlane_b32 s7, v254, 24
	s_nop 4
	global_load_dword v13, v0, s[6:7] sc1
	v_readlane_b32 s6, v254, 25
	v_readlane_b32 s7, v254, 26
	s_nop 4
	global_load_dword v14, v0, s[6:7] sc1
	v_readlane_b32 s6, v254, 27
	v_readlane_b32 s7, v254, 28
	s_nop 4
	global_load_dword v15, v0, s[6:7] sc1
	v_readlane_b32 s6, v254, 29
	v_readlane_b32 s7, v254, 30
	s_nop 4
	global_load_dword v16, v0, s[6:7] sc1
	s_waitcnt vmcnt(0)
	v_add_u32_e32 v17, v2, v1
	v_add_u32_e32 v17, v17, v3
	v_add_u32_e32 v17, v17, v4
	v_add_u32_e32 v17, v17, v5
	v_add_u32_e32 v17, v17, v6
	v_add_u32_e32 v17, v17, v7
	v_add_u32_e32 v17, v17, v8
	v_add_u32_e32 v17, v17, v9
	v_add_u32_e32 v17, v17, v10
	v_add_u32_e32 v17, v17, v11
	v_add_u32_e32 v17, v17, v12
	v_add_u32_e32 v17, v17, v13
	v_add_u32_e32 v17, v17, v14
	v_add_u32_e32 v17, v17, v15
	v_add_u32_e32 v17, v17, v16
	v_cmp_eq_u32_e32 vcc, s62, v17
	s_cbranch_vccnz .LBB0_486
	s_and_b32 s6, s5, 0xff
	s_cmp_eq_u32 s6, 0
	s_mov_b64 s[24:25], -1
	s_sleep 1
	s_cbranch_scc1 .LBB0_491
	s_and_b64 vcc, exec, s[24:25]
	s_cbranch_vccz .LBB0_486

; __device__ __forceinline__ unsigned xb_ld(unsigned* p)              { return __hip_atomic_load(p, __ATOMIC_RELAXED, __HIP_MEMORY_SCOPE_AGENT); }
; __device__ __forceinline__ void xcd_barrier_complete(unsigned* bar, unsigned x, unsigned& nloc, unsigned& nx) {
;     ...
;     for (;;) {
;         sum = 0u; cnt = 0u; mine = 0u;
; #pragma unroll
;         for (unsigned j = 0; j < 16; ++j) { const unsigned c = xb_ld(&bar[XB_XCNT(j)]); sum += c; cnt += (c > 0u) ? 1u : 0u; mine = (j == x) ? c : mine; }
;         if (sum == G) break;
;         __builtin_amdgcn_s_sleep(1);
;         if ((++sp & 255u) == 0u) { if (xb_ld(&bar[XB_TMO])) break; if (sp > XB_SPIN_CAP) { atomicAdd(&bar[XB_TMO], 1u); break; } }
;     }
.LBB0_692:
	v_readlane_b32 s6, v254, 1
	v_readlane_b32 s7, v254, 2
	global_load_dword v1, v0, s[8:9] sc1
	s_mov_b64 s[16:17], -1
	s_mov_b64 s[20:21], -1
	s_waitcnt lgkmcnt(0)
	s_nop 0
	global_load_dword v2, v0, s[6:7] sc1
	v_readlane_b32 s6, v254, 3
	v_readlane_b32 s7, v254, 4
	s_nop 4
	global_load_dword v3, v0, s[6:7] sc1
	v_readlane_b32 s6, v254, 5
	v_readlane_b32 s7, v254, 6
	s_nop 4
	global_load_dword v4, v0, s[6:7] sc1
	v_readlane_b32 s6, v254, 7
	v_readlane_b32 s7, v254, 8
	s_nop 4
	global_load_dword v5, v0, s[6:7] sc1
	v_readlane_b32 s6, v254, 9
	v_readlane_b32 s7, v254, 10
	s_nop 4
	global_load_dword v6, v0, s[6:7] sc1
	v_readlane_b32 s6, v254, 11
	v_readlane_b32 s7, v254, 12
	s_nop 4
	global_load_dword v7, v0, s[6:7] sc1
	v_readlane_b32 s6, v254, 13
	v_readlane_b32 s7, v254, 14
	s_nop 4
	global_load_dword v8, v0, s[6:7] sc1
	v_readlane_b32 s6, v254, 15
	v_readlane_b32 s7, v254, 16
	s_nop 4
	global_load_dword v9, v0, s[6:7] sc1
	v_readlane_b32 s6, v254, 17
	v_readlane_b32 s7, v254, 18
	s_nop 4
	global_load_dword v10, v0, s[6:7] sc1
	v_readlane_b32 s6, v254, 19
	v_readlane_b32 s7, v254, 20
	s_nop 4
	global_load_dword v11, v0, s[6:7] sc1
	v_readlane_b32 s6, v254, 21
	v_readlane_b32 s7, v254, 22
	s_nop 4
	global_load_dword v12, v0, s[6:7] sc1
	v_readlane_b32 s6, v254, 23
	v_readlane_b32 s7, v254, 24
	s_nop 4
	global_load_dword v13, v0, s[6:7] sc1
	v_readlane_b32 s6, v254, 25
	v_readlane_b32 s7, v254, 26
	s_nop 4
	global_load_dword v14, v0, s[6:7] sc1
	v_readlane_b32 s6, v254, 27
	v_readlane_b32 s7, v254, 28
	s_nop 4
	global_load_dword v15, v0, s[6:7] sc1
	v_readlane_b32 s6, v254, 29
	v_readlane_b32 s7, v254, 30
	s_nop 4
	global_load_dword v16, v0, s[6:7] sc1
	s_waitcnt vmcnt(0)
	v_add_u32_e32 v17, v2, v1
	v_add_u32_e32 v17, v17, v3
	v_add_u32_e32 v17, v17, v4
	v_add_u32_e32 v17, v17, v5
	v_add_u32_e32 v17, v17, v6
	v_add_u32_e32 v17, v17, v7
	v_add_u32_e32 v17, v17, v8
	v_add_u32_e32 v17, v17, v9
	v_add_u32_e32 v17, v17, v10
	v_add_u32_e32 v17, v17, v11
	v_add_u32_e32 v17, v17, v12
	v_add_u32_e32 v17, v17, v13
	v_add_u32_e32 v17, v17, v14
	v_add_u32_e32 v17, v17, v15
	v_add_u32_e32 v17, v17, v16
	v_cmp_eq_u32_e32 vcc, s62, v17
	s_cbranch_vccnz .LBB0_691
	s_and_b32 s6, s5, 0xff
	s_cmp_eq_u32 s6, 0
	s_mov_b64 s[24:25], -1
	s_sleep 1
	s_cbranch_scc1 .LBB0_696
	s_and_b64 vcc, exec, s[24:25]
	s_cbranch_vccz .LBB0_691

; __device__ __forceinline__ unsigned xb_ld(unsigned* p)              { return __hip_atomic_load(p, __ATOMIC_RELAXED, __HIP_MEMORY_SCOPE_AGENT); }
; __device__ __forceinline__ void xcd_barrier_complete(unsigned* bar, unsigned x, unsigned& nloc, unsigned& nx) {
;     ...
;     for (;;) {
;         sum = 0u; cnt = 0u; mine = 0u;
; #pragma unroll
;         for (unsigned j = 0; j < 16; ++j) { const unsigned c = xb_ld(&bar[XB_XCNT(j)]); sum += c; cnt += (c > 0u) ? 1u : 0u; mine = (j == x) ? c : mine; }
;         if (sum == G) break;
;         __builtin_amdgcn_s_sleep(1);
;         if ((++sp & 255u) == 0u) { if (xb_ld(&bar[XB_TMO])) break; if (sp > XB_SPIN_CAP) { atomicAdd(&bar[XB_TMO], 1u); break; } }
;     }
.LBB0_1054:
	v_readlane_b32 s8, v254, 1
	v_readlane_b32 s9, v254, 2
	global_load_dword v1, v0, s[60:61] sc1
	s_mov_b64 s[16:17], -1
	s_mov_b64 s[18:19], -1
	s_waitcnt lgkmcnt(0)
	s_nop 0
	global_load_dword v2, v0, s[8:9] sc1
	v_readlane_b32 s8, v254, 3
	v_readlane_b32 s9, v254, 4
	s_nop 4
	global_load_dword v3, v0, s[8:9] sc1
	v_readlane_b32 s8, v254, 5
	v_readlane_b32 s9, v254, 6
	s_nop 4
	global_load_dword v4, v0, s[8:9] sc1
	v_readlane_b32 s8, v254, 7
	v_readlane_b32 s9, v254, 8
	s_nop 4
	global_load_dword v5, v0, s[8:9] sc1
	v_readlane_b32 s8, v254, 9
	v_readlane_b32 s9, v254, 10
	s_nop 4
	global_load_dword v6, v0, s[8:9] sc1
	v_readlane_b32 s8, v254, 11
	v_readlane_b32 s9, v254, 12
	s_nop 4
	global_load_dword v7, v0, s[8:9] sc1
	v_readlane_b32 s8, v254, 13
	v_readlane_b32 s9, v254, 14
	s_nop 4
	global_load_dword v8, v0, s[8:9] sc1
	v_readlane_b32 s8, v254, 15
	v_readlane_b32 s9, v254, 16
	s_nop 4
	global_load_dword v9, v0, s[8:9] sc1
	v_readlane_b32 s8, v254, 17
	v_readlane_b32 s9, v254, 18
	s_nop 4
	global_load_dword v10, v0, s[8:9] sc1
	v_readlane_b32 s8, v254, 19
	v_readlane_b32 s9, v254, 20
	s_nop 4
	global_load_dword v11, v0, s[8:9] sc1
	v_readlane_b32 s8, v254, 21
	v_readlane_b32 s9, v254, 22
	s_nop 4
	global_load_dword v12, v0, s[8:9] sc1
	v_readlane_b32 s8, v254, 23
	v_readlane_b32 s9, v254, 24
	s_nop 4
	global_load_dword v13, v0, s[8:9] sc1
	v_readlane_b32 s8, v254, 25
	v_readlane_b32 s9, v254, 26
	s_nop 4
	global_load_dword v14, v0, s[8:9] sc1
	v_readlane_b32 s8, v254, 27
	v_readlane_b32 s9, v254, 28
	s_nop 4
	global_load_dword v15, v0, s[8:9] sc1
	v_readlane_b32 s8, v254, 29
	v_readlane_b32 s9, v254, 30
	s_nop 4
	global_load_dword v16, v0, s[8:9] sc1
	s_waitcnt vmcnt(0)
	v_add_u32_e32 v17, v2, v1
	v_add_u32_e32 v17, v17, v3
	v_add_u32_e32 v17, v17, v4
	v_add_u32_e32 v17, v17, v5
	v_add_u32_e32 v17, v17, v6
	v_add_u32_e32 v17, v17, v7
	v_add_u32_e32 v17, v17, v8
	v_add_u32_e32 v17, v17, v9
	v_add_u32_e32 v17, v17, v10
	v_add_u32_e32 v17, v17, v11
	v_add_u32_e32 v17, v17, v12
	v_add_u32_e32 v17, v17, v13
	v_add_u32_e32 v17, v17, v14
	v_add_u32_e32 v17, v17, v15
	v_add_u32_e32 v17, v17, v16
	v_cmp_eq_u32_e32 vcc, s62, v17
	s_cbranch_vccnz .LBB0_1053
	s_and_b32 s6, s5, 0xff
	s_cmp_eq_u32 s6, 0
	s_mov_b64 s[20:21], -1
	s_sleep 1
	s_cbranch_scc1 .LBB0_1058
	s_and_b64 vcc, exec, s[20:21]
	s_cbranch_vccz .LBB0_1053

; __device__ __forceinline__ unsigned xb_ld(unsigned* p)              { return __hip_atomic_load(p, __ATOMIC_RELAXED, __HIP_MEMORY_SCOPE_AGENT); }
; __device__ __forceinline__ void xcd_barrier_complete(unsigned* bar, unsigned x, unsigned& nloc, unsigned& nx) {
;     ...
;     for (;;) {
;         sum = 0u; cnt = 0u; mine = 0u;
; #pragma unroll
;         for (unsigned j = 0; j < 16; ++j) { const unsigned c = xb_ld(&bar[XB_XCNT(j)]); sum += c; cnt += (c > 0u) ? 1u : 0u; mine = (j == x) ? c : mine; }
;         if (sum == G) break;
;         __builtin_amdgcn_s_sleep(1);
;         if ((++sp & 255u) == 0u) { if (xb_ld(&bar[XB_TMO])) break; if (sp > XB_SPIN_CAP) { atomicAdd(&bar[XB_TMO], 1u); break; } }
;     }
.LBB0_1118:
	v_readlane_b32 s6, v254, 1
	v_readlane_b32 s7, v254, 2
	global_load_dword v1, v0, s[60:61] sc1
	s_mov_b64 s[16:17], -1
	s_mov_b64 s[18:19], -1
	s_waitcnt lgkmcnt(0)
	s_nop 0
	global_load_dword v2, v0, s[6:7] sc1
	v_readlane_b32 s6, v254, 3
	v_readlane_b32 s7, v254, 4
	s_nop 4
	global_load_dword v3, v0, s[6:7] sc1
	v_readlane_b32 s6, v254, 5
	v_readlane_b32 s7, v254, 6
	s_nop 4
	global_load_dword v4, v0, s[6:7] sc1
	v_readlane_b32 s6, v254, 7
	v_readlane_b32 s7, v254, 8
	s_nop 4
	global_load_dword v5, v0, s[6:7] sc1
	v_readlane_b32 s6, v254, 9
	v_readlane_b32 s7, v254, 10
	s_nop 4
	global_load_dword v6, v0, s[6:7] sc1
	v_readlane_b32 s6, v254, 11
	v_readlane_b32 s7, v254, 12
	s_nop 4
	global_load_dword v7, v0, s[6:7] sc1
	v_readlane_b32 s6, v254, 13
	v_readlane_b32 s7, v254, 14
	s_nop 4
	global_load_dword v8, v0, s[6:7] sc1
	v_readlane_b32 s6, v254, 15
	v_readlane_b32 s7, v254, 16
	s_nop 4
	global_load_dword v9, v0, s[6:7] sc1
	v_readlane_b32 s6, v254, 17
	v_readlane_b32 s7, v254, 18
	s_nop 4
	global_load_dword v10, v0, s[6:7] sc1
	v_readlane_b32 s6, v254, 19
	v_readlane_b32 s7, v254, 20
	s_nop 4
	global_load_dword v11, v0, s[6:7] sc1
	v_readlane_b32 s6, v254, 21
	v_readlane_b32 s7, v254, 22
	s_nop 4
	global_load_dword v12, v0, s[6:7] sc1
	v_readlane_b32 s6, v254, 23
	v_readlane_b32 s7, v254, 24
	s_nop 4
	global_load_dword v13, v0, s[6:7] sc1
	v_readlane_b32 s6, v254, 25
	v_readlane_b32 s7, v254, 26
	s_nop 4
	global_load_dword v14, v0, s[6:7] sc1
	v_readlane_b32 s6, v254, 27
	v_readlane_b32 s7, v254, 28
	s_nop 4
	global_load_dword v15, v0, s[6:7] sc1
	v_readlane_b32 s6, v254, 29
	v_readlane_b32 s7, v254, 30
	s_nop 4
	global_load_dword v16, v0, s[6:7] sc1
	s_waitcnt vmcnt(0)
	v_add_u32_e32 v17, v2, v1
	v_add_u32_e32 v17, v17, v3
	v_add_u32_e32 v17, v17, v4
	v_add_u32_e32 v17, v17, v5
	v_add_u32_e32 v17, v17, v6
	v_add_u32_e32 v17, v17, v7
	v_add_u32_e32 v17, v17, v8
	v_add_u32_e32 v17, v17, v9
	v_add_u32_e32 v17, v17, v10
	v_add_u32_e32 v17, v17, v11
	v_add_u32_e32 v17, v17, v12
	v_add_u32_e32 v17, v17, v13
	v_add_u32_e32 v17, v17, v14
	v_add_u32_e32 v17, v17, v15
	v_add_u32_e32 v17, v17, v16
	v_cmp_eq_u32_e32 vcc, s62, v17
	s_cbranch_vccnz .LBB0_1117
	s_and_b32 s6, s5, 0xff
	s_cmp_eq_u32 s6, 0
	s_mov_b64 s[20:21], -1
	s_sleep 1
	s_cbranch_scc1 .LBB0_1122
	s_and_b64 vcc, exec, s[20:21]
	s_cbranch_vccz .LBB0_1117
